# P2: all workgroups run the GEMMs first and HGRN pass A last (no odd/even interleave)
# speedup vs baseline: 1.0275x; 1.0007x over previous
.LBB0_199:
	s_bitcmp0_b32 s64, 0
	s_cselect_b64 s[94:95], -1, 0
	s_cmp_lt_i32 s20, 1
	s_cselect_b64 s[2:3], -1, 0
	s_mov_b64 s[2:3], -1
	s_mov_b32 s1, 0
	s_and_b64 vcc, exec, s[2:3]
	s_cbranch_vccnz .LBB0_222
	s_cmp_lt_i32 s64, 64
	s_cselect_b32 s0, 64, 0xffffffc0
	s_add_i32 s8, s64, s0
	s_addk_i32 s8, 0x700
	s_add_u32 s34, s90, 0x1e800000
	s_addc_u32 s35, s91, 0
	v_readlane_b32 s2, v246, 36
	s_add_u32 s56, s90, 0x1ea00000
	v_readlane_b32 s3, v246, 37
	s_addc_u32 s57, s91, 0
	s_movk_i32 s9, 0x2880
	v_mov_b64_e32 v[32:33], s[2:3]
	s_movk_i32 s10, 0x1000
	s_mov_b32 s11, 0x800000
	s_mov_b32 s16, 0x3f317217
	s_mov_b32 s17, 0x7f800000
	v_mov_b32_e32 v46, 0x41b17218
	s_movk_i32 s18, 0x7f
	s_movk_i32 s19, 0x2040
	s_add_i32 s21, 0, 0x8100
	s_movk_i32 s22, 0x480
	s_movk_i32 s23, 0x48
	v_mov_b32_e32 v35, 0
	s_movk_i32 s24, 0x90
	s_mov_b32 s25, 0
	s_mov_b32 s99, s64
	s_lshl_b32 s100, s99, 3
	s_lshl_b32 s101, s99, 6
	s_and_b32 s100, s100, 0xffffe000
	s_and_b32 s101, s101, 0x1fc0
	s_or_b32 s100, s100, s101
	s_and_b32 s98, s99, 0x380
	v_ashrrev_i32_e32 v206, 6, v210
	v_bfi_b32 v208, -4, v206, v210
	v_lshlrev_b32_e32 v208, 4, v208
	v_mov_b32_e32 v209, 0
	v_bfe_u32 v206, v210, 2, 6
	v_or_b32_e32 v206, s100, v206
	v_mad_i64_i32 v[200:201], vcc, v206, s9, v[32:33]
	s_lshl_b32 s100, s98, 1
	s_mov_b32 s101, 0
	v_lshl_add_u64 v[200:201], v[200:201], 0, s[100:101]
	v_lshl_add_u64 v[200:201], v[208:209], 1, v[200:201]
	v_add_u32_e32 v202, s98, v208
	v_mov_b32_e32 v203, 0
	v_lshl_add_u64 v[202:203], v[202:203], 2, s[54:55]
	s_movk_i32 s100, 0x1000
	v_lshl_add_u64 v[204:205], v[200:201], 0, s[100:101]
	global_load_dwordx4 v[160:163], v[200:201], off offset:2048
	global_load_dwordx4 v[164:167], v[200:201], off offset:2064
	global_load_dwordx4 v[168:171], v[202:203], off
	global_load_dwordx4 v[172:175], v[202:203], off offset:16
	global_load_dwordx4 v[176:179], v[200:201], off offset:16
	global_load_dwordx4 v[180:183], v[200:201], off
	global_load_dwordx4 v[184:187], v[204:205], off
	global_load_dwordx4 v[188:191], v[204:205], off offset:16
	global_load_dwordx4 v[192:195], v[202:203], off offset:48
	global_load_dwordx4 v[196:199], v[202:203], off offset:32
	s_waitcnt vmcnt(0)
	s_branch .LBB0_202

.LBB0_394:
	s_cmp_gt_i32 s20, 0
	s_cselect_b64 s[2:3], -1, 0
	s_nop 0
	s_andn2_b64 vcc, exec, s[2:3]
	s_mov_b32 s15, 0
	s_cbranch_vccnz .LBB0_417
	s_add_i32 s2, s64, 64
	s_and_b64 s[0:1], s[0:1], exec
	s_cselect_b32 s8, s2, s10
	s_addk_i32 s8, 0x700
	s_add_u32 s0, s90, 0x1e800000
	s_addc_u32 s1, s91, 0
	v_readlane_b32 s2, v246, 36
	s_add_u32 s34, s90, 0x1ea00000
	v_readlane_b32 s3, v246, 37
	s_addc_u32 s35, s91, 0
	s_movk_i32 s9, 0x2880
	v_mov_b64_e32 v[32:33], s[2:3]
	s_movk_i32 s10, 0x1000
	s_mov_b32 s11, 0x800000
	s_mov_b32 s16, 0x3f317217
	s_mov_b32 s17, 0x7f800000
	v_mov_b32_e32 v46, 0x41b17218
	s_movk_i32 s18, 0x7f
	s_movk_i32 s19, 0x2040
	s_add_i32 s21, 0, 0x8100
	s_movk_i32 s22, 0x480
	s_movk_i32 s23, 0x48
	v_mov_b32_e32 v35, 0
	s_movk_i32 s24, 0x90
	s_mov_b32 s25, 0
	s_mov_b32 s99, s64
	s_lshl_b32 s100, s99, 3
	s_lshl_b32 s101, s99, 6
	s_and_b32 s100, s100, 0xffffe000
	s_and_b32 s101, s101, 0x1fc0
	s_or_b32 s100, s100, s101
	s_and_b32 s98, s99, 0x380
	v_ashrrev_i32_e32 v206, 6, v210
	v_bfi_b32 v208, -4, v206, v210
	v_lshlrev_b32_e32 v208, 4, v208
	v_mov_b32_e32 v209, 0
	v_bfe_u32 v206, v210, 2, 6
	v_or_b32_e32 v206, s100, v206
	v_mad_i64_i32 v[200:201], vcc, v206, s9, v[32:33]
	s_lshl_b32 s100, s98, 1
	s_mov_b32 s101, 0
	v_lshl_add_u64 v[200:201], v[200:201], 0, s[100:101]
	v_lshl_add_u64 v[200:201], v[208:209], 1, v[200:201]
	v_add_u32_e32 v202, s98, v208
	v_mov_b32_e32 v203, 0
	v_lshl_add_u64 v[202:203], v[202:203], 2, s[54:55]
	s_movk_i32 s100, 0x1000
	v_lshl_add_u64 v[204:205], v[200:201], 0, s[100:101]
	global_load_dwordx4 v[160:163], v[200:201], off offset:2048
	global_load_dwordx4 v[164:167], v[200:201], off offset:2064
	global_load_dwordx4 v[168:171], v[202:203], off
	global_load_dwordx4 v[172:175], v[202:203], off offset:16
	global_load_dwordx4 v[176:179], v[200:201], off offset:16
	global_load_dwordx4 v[180:183], v[200:201], off
	global_load_dwordx4 v[184:187], v[204:205], off
	global_load_dwordx4 v[188:191], v[204:205], off offset:16
	global_load_dwordx4 v[192:195], v[202:203], off offset:48
	global_load_dwordx4 v[196:199], v[202:203], off offset:32
	s_waitcnt vmcnt(0)
	s_branch .LBB0_397
